# v53: v41 + P1 low-rank column tile skips the MFMA runs whose accumulators are never stored (block-2 runs in all waves, block-1 runs in waves without columns <16); power-saving only
# baseline (speedup 1.0000x reference)
.LBB0_374:
	s_cmp_eq_u64 s[2:3], 0
	s_cselect_b32 s32, 3, 1
	s_cmp_eq_u32 s8, 14
	s_cselect_b32 s32, s32, 0
	ds_read_b128 v[152:155], v157
	ds_read_b128 v[160:163], v157 offset:1024
	ds_read_b128 v[164:167], v157 offset:2048
	ds_read_b128 v[168:171], v157 offset:3072
	ds_read_b128 v[172:175], v158
	ds_read_b128 v[176:179], v158 offset:1024
	ds_read_b128 v[180:183], v158 offset:2048
	ds_read_b128 v[184:187], v158 offset:3072
	s_add_u32 s28, s26, 0xfffc0080
	s_addc_u32 s29, s27, -1
	s_cmp_eq_u32 s80, 12
	s_cselect_b32 s31, s7, s29
	s_cselect_b32 s30, s21, s28
	s_cselect_b32 s29, s19, s59
	s_cselect_b32 s28, s57, s58
	v_lshl_add_u64 v[222:223], s[26:27], 0, v[144:145]
	s_add_i32 m0, s9, 0xc000
	ds_read_b128 v[188:191], v159
	ds_read_b128 v[192:195], v159 offset:1024
	ds_read_b128 v[196:199], v159 offset:2048
	ds_read_b128 v[200:203], v159 offset:3072
	ds_read_b128 v[204:207], v159 offset:4096
	ds_read_b128 v[210:213], v159 offset:5120
	ds_read_b128 v[214:217], v159 offset:6144
	ds_read_b128 v[218:221], v159 offset:7168
	global_load_lds_dwordx4 v[222:223], off
	v_lshl_add_u64 v[222:223], s[26:27], 0, v[146:147]
	s_add_i32 m0, s9, 0xe000
	s_nop 0
	global_load_lds_dwordx4 v[222:223], off
	s_waitcnt vmcnt(8)
	s_waitcnt lgkmcnt(0)
	s_barrier
	s_setprio 1
	s_waitcnt lgkmcnt(0)
	s_bitcmp1_b32 s32, 1
	s_cbranch_scc1 .Lp1sk_0
	v_mfma_f32_16x16x32_bf16 v[126:129], v[152:155], v[188:191], v[126:129]
	v_mfma_f32_16x16x32_bf16 v[122:125], v[164:167], v[188:191], v[122:125]
	v_mfma_f32_16x16x32_bf16 v[110:113], v[152:155], v[196:199], v[110:113]
	v_mfma_f32_16x16x32_bf16 v[106:109], v[164:167], v[196:199], v[106:109]
	v_mfma_f32_16x16x32_bf16 v[94:97], v[152:155], v[204:207], v[94:97]
	v_mfma_f32_16x16x32_bf16 v[90:93], v[164:167], v[204:207], v[90:93]
	v_mfma_f32_16x16x32_bf16 v[78:81], v[152:155], v[214:217], v[78:81]
	v_mfma_f32_16x16x32_bf16 v[74:77], v[164:167], v[214:217], v[74:77]
	v_mfma_f32_16x16x32_bf16 v[126:129], v[160:163], v[192:195], v[126:129]
	v_mfma_f32_16x16x32_bf16 v[122:125], v[168:171], v[192:195], v[122:125]
	v_mfma_f32_16x16x32_bf16 v[110:113], v[160:163], v[200:203], v[110:113]
	v_mfma_f32_16x16x32_bf16 v[106:109], v[168:171], v[200:203], v[106:109]
	v_mfma_f32_16x16x32_bf16 v[94:97], v[160:163], v[210:213], v[94:97]
	v_mfma_f32_16x16x32_bf16 v[90:93], v[168:171], v[210:213], v[90:93]
	v_mfma_f32_16x16x32_bf16 v[78:81], v[160:163], v[218:221], v[78:81]
	v_mfma_f32_16x16x32_bf16 v[74:77], v[168:171], v[218:221], v[74:77]
.Lp1sk_0:
	s_setprio 0
	s_setprio 1
	s_bitcmp1_b32 s32, 0
	s_cbranch_scc1 .Lp1sk_1
	v_mfma_f32_16x16x32_bf16 v[118:121], v[172:175], v[188:191], v[118:121]
	v_mfma_f32_16x16x32_bf16 v[114:117], v[180:183], v[188:191], v[114:117]
	v_mfma_f32_16x16x32_bf16 v[102:105], v[172:175], v[196:199], v[102:105]
	v_mfma_f32_16x16x32_bf16 v[98:101], v[180:183], v[196:199], v[98:101]
	v_mfma_f32_16x16x32_bf16 v[86:89], v[172:175], v[204:207], v[86:89]
	v_mfma_f32_16x16x32_bf16 v[82:85], v[180:183], v[204:207], v[82:85]
	v_mfma_f32_16x16x32_bf16 v[70:73], v[172:175], v[214:217], v[70:73]
	v_mfma_f32_16x16x32_bf16 v[66:69], v[180:183], v[214:217], v[66:69]
	v_mfma_f32_16x16x32_bf16 v[118:121], v[176:179], v[192:195], v[118:121]
	v_mfma_f32_16x16x32_bf16 v[114:117], v[184:187], v[192:195], v[114:117]
	v_mfma_f32_16x16x32_bf16 v[102:105], v[176:179], v[200:203], v[102:105]
	v_mfma_f32_16x16x32_bf16 v[98:101], v[184:187], v[200:203], v[98:101]
	v_mfma_f32_16x16x32_bf16 v[86:89], v[176:179], v[210:213], v[86:89]
	v_mfma_f32_16x16x32_bf16 v[82:85], v[184:187], v[210:213], v[82:85]
	v_mfma_f32_16x16x32_bf16 v[70:73], v[176:179], v[218:221], v[70:73]
	v_mfma_f32_16x16x32_bf16 v[66:69], v[184:187], v[218:221], v[66:69]
.Lp1sk_1:
	s_setprio 0
	s_barrier
	s_add_i32 s81, s44, s35
	v_lshl_add_u64 v[222:223], s[28:29], 0, v[132:133]
	s_mov_b32 m0, s81
	ds_read_b128 v[188:191], v159 offset:16384
	ds_read_b128 v[192:195], v159 offset:17408
	ds_read_b128 v[196:199], v159 offset:18432
	ds_read_b128 v[200:203], v159 offset:19456
	ds_read_b128 v[204:207], v159 offset:20480
	ds_read_b128 v[210:213], v159 offset:21504
	ds_read_b128 v[214:217], v159 offset:22528
	ds_read_b128 v[218:221], v159 offset:23552
	global_load_lds_dwordx4 v[222:223], off
	s_add_i32 m0, s81, 0x2000
	s_add_u32 s82, s28, 0x40000
	v_lshl_add_u64 v[224:225], s[28:29], 0, v[136:137]
	s_addc_u32 s83, s29, 0
	s_add_i32 s81, s45, s35
	global_load_lds_dwordx4 v[224:225], off
	v_lshl_add_u64 v[226:227], s[82:83], 0, v[132:133]
	s_mov_b32 m0, s81
	v_lshl_add_u64 v[228:229], s[30:31], 0, v[134:135]
	global_load_lds_dwordx4 v[226:227], off
	v_lshl_add_u64 v[226:227], s[82:83], 0, v[136:137]
	s_add_i32 m0, s81, 0x2000
	s_nop 0
	global_load_lds_dwordx4 v[226:227], off
	v_lshl_add_u64 v[226:227], s[30:31], 0, v[130:131]
	s_mov_b32 m0, s9
	s_nop 0
	global_load_lds_dwordx4 v[226:227], off
	s_mov_b32 m0, s36
	s_nop 0
	global_load_lds_dwordx4 v[228:229], off
	s_waitcnt vmcnt(8)
	s_waitcnt lgkmcnt(0)
	s_barrier
	s_setprio 1
	s_waitcnt lgkmcnt(0)
	s_bitcmp1_b32 s32, 1
	s_cbranch_scc1 .Lp1sk_2
	v_mfma_f32_16x16x32_bf16 v[62:65], v[152:155], v[188:191], v[62:65]
	v_mfma_f32_16x16x32_bf16 v[58:61], v[164:167], v[188:191], v[58:61]
	v_mfma_f32_16x16x32_bf16 v[46:49], v[152:155], v[196:199], v[46:49]
	v_mfma_f32_16x16x32_bf16 v[42:45], v[164:167], v[196:199], v[42:45]
	v_mfma_f32_16x16x32_bf16 v[30:33], v[152:155], v[204:207], v[30:33]
	v_mfma_f32_16x16x32_bf16 v[26:29], v[164:167], v[204:207], v[26:29]
	v_mfma_f32_16x16x32_bf16 v[14:17], v[152:155], v[214:217], v[14:17]
	v_mfma_f32_16x16x32_bf16 v[10:13], v[164:167], v[214:217], v[10:13]
	v_mfma_f32_16x16x32_bf16 v[62:65], v[160:163], v[192:195], v[62:65]
	v_mfma_f32_16x16x32_bf16 v[58:61], v[168:171], v[192:195], v[58:61]
	v_mfma_f32_16x16x32_bf16 v[46:49], v[160:163], v[200:203], v[46:49]
	v_mfma_f32_16x16x32_bf16 v[42:45], v[168:171], v[200:203], v[42:45]
	v_mfma_f32_16x16x32_bf16 v[30:33], v[160:163], v[210:213], v[30:33]
	v_mfma_f32_16x16x32_bf16 v[26:29], v[168:171], v[210:213], v[26:29]
	v_mfma_f32_16x16x32_bf16 v[14:17], v[160:163], v[218:221], v[14:17]
	v_mfma_f32_16x16x32_bf16 v[10:13], v[168:171], v[218:221], v[10:13]
.Lp1sk_2:
	s_setprio 0
	s_setprio 1
	s_bitcmp1_b32 s32, 0
	s_cbranch_scc1 .Lp1sk_3
	v_mfma_f32_16x16x32_bf16 v[54:57], v[172:175], v[188:191], v[54:57]
	v_mfma_f32_16x16x32_bf16 v[50:53], v[180:183], v[188:191], v[50:53]
	v_mfma_f32_16x16x32_bf16 v[38:41], v[172:175], v[196:199], v[38:41]
	v_mfma_f32_16x16x32_bf16 v[34:37], v[180:183], v[196:199], v[34:37]
	v_mfma_f32_16x16x32_bf16 v[22:25], v[172:175], v[204:207], v[22:25]
	v_mfma_f32_16x16x32_bf16 v[18:21], v[180:183], v[204:207], v[18:21]
	v_mfma_f32_16x16x32_bf16 v[6:9], v[172:175], v[214:217], v[6:9]
	v_mfma_f32_16x16x32_bf16 v[2:5], v[180:183], v[214:217], v[2:5]
	v_mfma_f32_16x16x32_bf16 v[54:57], v[176:179], v[192:195], v[54:57]
	v_mfma_f32_16x16x32_bf16 v[50:53], v[184:187], v[192:195], v[50:53]
	v_mfma_f32_16x16x32_bf16 v[38:41], v[176:179], v[200:203], v[38:41]
	v_mfma_f32_16x16x32_bf16 v[34:37], v[184:187], v[200:203], v[34:37]
	v_mfma_f32_16x16x32_bf16 v[22:25], v[176:179], v[210:213], v[22:25]
	v_mfma_f32_16x16x32_bf16 v[18:21], v[184:187], v[210:213], v[18:21]
	v_mfma_f32_16x16x32_bf16 v[6:9], v[176:179], v[218:221], v[6:9]
	v_mfma_f32_16x16x32_bf16 v[2:5], v[184:187], v[218:221], v[2:5]
.Lp1sk_3:
	s_setprio 0
	s_barrier
	s_add_i32 s81, 0, 0x18000
	v_add_u32_e32 v138, s81, v156
	s_add_i32 s82, 0, 0x1c000
	ds_read_b128 v[152:155], v138
	ds_read_b128 v[160:163], v138 offset:1024
	ds_read_b128 v[164:167], v138 offset:2048
	ds_read_b128 v[168:171], v138 offset:3072
	v_add_u32_e32 v138, 0x1000, v138
	ds_read_b128 v[172:175], v138
	ds_read_b128 v[176:179], v138 offset:1024
	ds_read_b128 v[180:183], v138 offset:2048
	ds_read_b128 v[184:187], v138 offset:3072
	s_add_u32 s30, s30, 0x40000
	s_addc_u32 s31, s31, 0
	s_mov_b32 m0, s37
	v_lshl_add_u64 v[230:231], s[30:31], 0, v[130:131]
	ds_read_b128 v[188:191], v159 offset:32768
	ds_read_b128 v[192:195], v159 offset:33792
	ds_read_b128 v[196:199], v159 offset:34816
	ds_read_b128 v[200:203], v159 offset:35840
	ds_read_b128 v[204:207], v159 offset:36864
	ds_read_b128 v[210:213], v159 offset:37888
	ds_read_b128 v[214:217], v159 offset:38912
	ds_read_b128 v[218:221], v159 offset:39936
	global_load_lds_dwordx4 v[230:231], off
	v_lshl_add_u64 v[230:231], s[30:31], 0, v[134:135]
	s_mov_b32 m0, s38
	s_nop 0
	global_load_lds_dwordx4 v[230:231], off
	s_waitcnt vmcnt(8)
	s_waitcnt lgkmcnt(0)
	s_barrier
	s_setprio 1
	s_waitcnt lgkmcnt(0)
	s_bitcmp1_b32 s32, 1
	s_cbranch_scc1 .Lp1sk_4
	v_mfma_f32_16x16x32_bf16 v[126:129], v[152:155], v[188:191], v[126:129]
	v_mfma_f32_16x16x32_bf16 v[122:125], v[164:167], v[188:191], v[122:125]
	v_mfma_f32_16x16x32_bf16 v[110:113], v[152:155], v[196:199], v[110:113]
	v_mfma_f32_16x16x32_bf16 v[106:109], v[164:167], v[196:199], v[106:109]
	v_mfma_f32_16x16x32_bf16 v[94:97], v[152:155], v[204:207], v[94:97]
	v_mfma_f32_16x16x32_bf16 v[90:93], v[164:167], v[204:207], v[90:93]
	v_mfma_f32_16x16x32_bf16 v[78:81], v[152:155], v[214:217], v[78:81]
	v_mfma_f32_16x16x32_bf16 v[74:77], v[164:167], v[214:217], v[74:77]
	v_mfma_f32_16x16x32_bf16 v[126:129], v[160:163], v[192:195], v[126:129]
	v_mfma_f32_16x16x32_bf16 v[122:125], v[168:171], v[192:195], v[122:125]
	v_mfma_f32_16x16x32_bf16 v[110:113], v[160:163], v[200:203], v[110:113]
	v_mfma_f32_16x16x32_bf16 v[106:109], v[168:171], v[200:203], v[106:109]
	v_mfma_f32_16x16x32_bf16 v[94:97], v[160:163], v[210:213], v[94:97]
	v_mfma_f32_16x16x32_bf16 v[90:93], v[168:171], v[210:213], v[90:93]
	v_mfma_f32_16x16x32_bf16 v[78:81], v[160:163], v[218:221], v[78:81]
	v_mfma_f32_16x16x32_bf16 v[74:77], v[168:171], v[218:221], v[74:77]

.Lp1sk_5:
	s_setprio 0
	s_barrier
	s_add_i32 s30, s81, s35
	v_lshl_add_u64 v[222:223], v[222:223], 0, s[14:15]
	s_mov_b32 m0, s30
	ds_read_b128 v[188:191], v159 offset:49152
	ds_read_b128 v[192:195], v159 offset:50176
	ds_read_b128 v[196:199], v159 offset:51200
	ds_read_b128 v[200:203], v159 offset:52224
	ds_read_b128 v[204:207], v159 offset:53248
	ds_read_b128 v[210:213], v159 offset:54272
	ds_read_b128 v[214:217], v159 offset:55296
	ds_read_b128 v[218:221], v159 offset:56320
	global_load_lds_dwordx4 v[222:223], off
	s_add_i32 m0, s30, 0x2000
	s_add_u32 s28, s28, 0x40080
	v_lshl_add_u64 v[222:223], v[224:225], 0, s[14:15]
	s_addc_u32 s29, s29, 0
	s_add_i32 s30, s82, s35
	global_load_lds_dwordx4 v[222:223], off
	v_lshl_add_u64 v[222:223], s[28:29], 0, v[132:133]
	s_mov_b32 m0, s30
	s_nop 0
	global_load_lds_dwordx4 v[222:223], off
	v_lshl_add_u64 v[222:223], s[28:29], 0, v[136:137]
	s_add_i32 m0, s30, 0x2000
	s_nop 0
	global_load_lds_dwordx4 v[222:223], off
	v_lshl_add_u64 v[222:223], v[226:227], 0, s[14:15]
	s_mov_b32 m0, s40
	s_nop 0
	global_load_lds_dwordx4 v[222:223], off
	v_lshl_add_u64 v[222:223], v[228:229], 0, s[14:15]
	s_mov_b32 m0, s41
	s_nop 0
	global_load_lds_dwordx4 v[222:223], off
	s_waitcnt vmcnt(8)
	s_waitcnt lgkmcnt(0)
	s_barrier
	s_setprio 1
	s_waitcnt lgkmcnt(0)
	s_bitcmp1_b32 s32, 1
	s_cbranch_scc1 .Lp1sk_6
	v_mfma_f32_16x16x32_bf16 v[62:65], v[152:155], v[188:191], v[62:65]
	v_mfma_f32_16x16x32_bf16 v[58:61], v[164:167], v[188:191], v[58:61]
	v_mfma_f32_16x16x32_bf16 v[46:49], v[152:155], v[196:199], v[46:49]
	v_mfma_f32_16x16x32_bf16 v[42:45], v[164:167], v[196:199], v[42:45]
	v_mfma_f32_16x16x32_bf16 v[30:33], v[152:155], v[204:207], v[30:33]
	v_mfma_f32_16x16x32_bf16 v[26:29], v[164:167], v[204:207], v[26:29]
	v_mfma_f32_16x16x32_bf16 v[14:17], v[152:155], v[214:217], v[14:17]
	v_mfma_f32_16x16x32_bf16 v[10:13], v[164:167], v[214:217], v[10:13]
	v_mfma_f32_16x16x32_bf16 v[62:65], v[160:163], v[192:195], v[62:65]
	v_mfma_f32_16x16x32_bf16 v[58:61], v[168:171], v[192:195], v[58:61]
	v_mfma_f32_16x16x32_bf16 v[46:49], v[160:163], v[200:203], v[46:49]
	v_mfma_f32_16x16x32_bf16 v[42:45], v[168:171], v[200:203], v[42:45]
	v_mfma_f32_16x16x32_bf16 v[30:33], v[160:163], v[210:213], v[30:33]
	v_mfma_f32_16x16x32_bf16 v[26:29], v[168:171], v[210:213], v[26:29]
	v_mfma_f32_16x16x32_bf16 v[14:17], v[160:163], v[218:221], v[14:17]
	v_mfma_f32_16x16x32_bf16 v[10:13], v[168:171], v[218:221], v[10:13]

.Lp1sk_7:
	s_setprio 0
	s_barrier
	s_add_i32 s80, s80, 2
	s_add_u32 s26, s26, 0x100
	s_addc_u32 s27, s27, 0
	s_add_u32 s58, s58, 0x100
	s_addc_u32 s59, s59, 0
	s_cmp_gt_u32 s80, 13
	s_cbranch_scc0 .LBB0_374
	s_and_b64 vcc, exec, s[16:17]
	s_cbranch_vccz .LBB0_377
	s_barrier
